# v-pass: per-lane-half gate weights read straight from LDS (no select), issued early with counted waits
# baseline (speedup 1.0000x reference)
; #define FP4_AXPY(k) { acc2[k] += w * __builtin_amdgcn_cvt_scalef32_pk_f32_fp4(vr[q].x, 1.0f, k); acc2[4 + k] += w * __builtin_amdgcn_cvt_scalef32_pk_f32_fp4(vr[q].y, 1.0f, k); \
;                       acc2[8 + k] += w * __builtin_amdgcn_cvt_scalef32_pk_f32_fp4(vr[q].z, 1.0f, k); acc2[12 + k] += w * __builtin_amdgcn_cvt_scalef32_pk_f32_fp4(vr[q].w, 1.0f, k); }
; __device__ __forceinline__ void peer_token(const Params& P, int t, int lane, int* sidx, float* sval, const int* sid, const float* sgate, const unsigned* szero) {
;     ...
; #pragma unroll 1
;     for (int e0 = 0; e0 < 128; e0 += 16) {
;         uint4 vr[8];
; #pragma unroll
;         for (int q = 0; q < 8; ++q) vr[q] = *(const uint4*)(Vb + ((unsigned)sid[e0 + 2 * q + half] * 512u + vlo));
;         const float* sw = (const float*)sidx + e0;
;         const f32x4 w0 = *(const f32x4*)(sw), w1 = *(const f32x4*)(sw + 4), w2 = *(const f32x4*)(sw + 8), w3 = *(const f32x4*)(sw + 12);
;         const float wq[16] = {w0[0], w0[1], w0[2], w0[3], w1[0], w1[1], w1[2], w1[3], w2[0], w2[1], w2[2], w2[3], w3[0], w3[1], w3[2], w3[3]};
; #pragma unroll
;         for (int q = 0; q < 8; ++q) {
;             const float w = half ? wq[2 * q + 1] : wq[2 * q];
;     ...
;             FP4_AXPY(0) FP4_AXPY(1) FP4_AXPY(2) FP4_AXPY(3)
;     ...
;         }
.Lp5_v_head:
	s_mul_i32 s16, s85, s22
	v_add_u32_e32 v112, s16, v130
	v_cmp_gt_i32_e32 vcc, s20, v112
	s_and_saveexec_b64 s[16:17], vcc
	s_cbranch_execz .Lp5_v_next
	v_ashrrev_i32_e32 v113, 31, v112
	v_lshlrev_b64 v[0:1], 11, v[112:113]
	v_lshl_add_u64 v[110:111], s[36:37], 0, v[0:1]
	v_lshl_add_u32 v139, s85, 10, v114
	v_mov_b32_e32 v42, 0
	v_lshlrev_b64 v[40:41], 10, v[112:113]
	s_mov_b32 s18, -16
	v_add_u32_e32 v74, v139, v128
	v_mov_b32_e32 v43, v42
	v_mov_b32_e32 v68, v42
	v_mov_b32_e32 v69, v42
	v_mov_b32_e32 v66, v42
	v_mov_b32_e32 v67, v42
	v_mov_b32_e32 v70, v42
	v_mov_b32_e32 v71, v42
	v_mov_b32_e32 v72, v42
	v_mov_b32_e32 v73, v42
	v_mov_b32_e32 v58, v42
	v_mov_b32_e32 v59, v42
	v_mov_b32_e32 v60, v42
	v_mov_b32_e32 v61, v42
	v_mov_b32_e32 v62, v42
	v_mov_b32_e32 v63, v42
	v_mov_b32_e32 v64, v42
	v_mov_b32_e32 v65, v42
	v_mov_b32_e32 v50, v42
	v_mov_b32_e32 v51, v42
	v_mov_b32_e32 v52, v42
	v_mov_b32_e32 v53, v42
	v_mov_b32_e32 v54, v42
	v_mov_b32_e32 v55, v42
	v_mov_b32_e32 v56, v42
	v_mov_b32_e32 v57, v42
	v_mov_b32_e32 v44, v42
	v_mov_b32_e32 v45, v42
	v_mov_b32_e32 v46, v42
	v_mov_b32_e32 v47, v42
	v_mov_b32_e32 v48, v42
	v_mov_b32_e32 v49, v42
.LBB0_1424:
	ds_read2_b32 v[0:1], v74 offset1:2
	ds_read2_b32 v[2:3], v74 offset0:4 offset1:6
	ds_read2_b32 v[4:5], v74 offset0:8 offset1:10
	ds_read2_b32 v[6:7], v74 offset0:12 offset1:14
	ds_read_b32 v80, v74 offset:512
	ds_read_b32 v82, v74 offset:520
	ds_read_b32 v28, v74 offset:528
	ds_read_b32 v30, v74 offset:536
	ds_read_b32 v16, v74 offset:544
	ds_read_b32 v18, v74 offset:552
	s_add_i32 s18, s18, 16
	s_waitcnt lgkmcnt(9)
	v_lshl_or_b32 v0, v0, 9, v122
	global_load_dwordx4 v[76:79], v0, s[14:15]
	v_lshl_or_b32 v0, v1, 9, v122
	global_load_dwordx4 v[36:39], v0, s[14:15]
	s_waitcnt lgkmcnt(8)
	v_lshl_or_b32 v0, v2, 9, v122
	global_load_dwordx4 v[32:35], v0, s[14:15]
	v_lshl_or_b32 v0, v3, 9, v122
	global_load_dwordx4 v[24:27], v0, s[14:15]
	s_waitcnt lgkmcnt(7)
	v_lshl_or_b32 v0, v4, 9, v122
	global_load_dwordx4 v[20:23], v0, s[14:15]
	v_lshl_or_b32 v0, v5, 9, v122
	global_load_dwordx4 v[12:15], v0, s[14:15]
	s_waitcnt lgkmcnt(6)
	v_lshl_or_b32 v0, v6, 9, v122
	global_load_dwordx4 v[8:11], v0, s[14:15]
	v_lshl_or_b32 v0, v7, 9, v122
	global_load_dwordx4 v[0:3], v0, s[14:15]
	ds_read_b32 v4, v74 offset:560
	ds_read_b32 v6, v74 offset:568
	v_add_u32_e32 v74, 64, v74
	s_waitcnt lgkmcnt(2)
	s_cmpk_lt_u32 s18, 0x70
	s_waitcnt vmcnt(7)
	v_cvt_scalef32_pk_f32_fp4 v[84:85], v76, 1.0
	v_pk_fma_f32 v[68:69], v[80:81], v[84:85], v[68:69] op_sel_hi:[0,1,1]
	v_cvt_scalef32_pk_f32_fp4 v[84:85], v77, 1.0
	v_pk_fma_f32 v[58:59], v[80:81], v[84:85], v[58:59] op_sel_hi:[0,1,1]
	v_cvt_scalef32_pk_f32_fp4 v[84:85], v78, 1.0
	v_pk_fma_f32 v[50:51], v[80:81], v[84:85], v[50:51] op_sel_hi:[0,1,1]
	v_cvt_scalef32_pk_f32_fp4 v[84:85], v79, 1.0
	v_pk_fma_f32 v[44:45], v[80:81], v[84:85], v[44:45] op_sel_hi:[0,1,1]
	v_cvt_scalef32_pk_f32_fp4 v[84:85], v76, 1.0 op_sel:[1,0,0]
	v_pk_fma_f32 v[66:67], v[80:81], v[84:85], v[66:67] op_sel_hi:[0,1,1]
	v_cvt_scalef32_pk_f32_fp4 v[84:85], v77, 1.0 op_sel:[1,0,0]
	v_pk_fma_f32 v[60:61], v[80:81], v[84:85], v[60:61] op_sel_hi:[0,1,1]
	v_cvt_scalef32_pk_f32_fp4 v[84:85], v78, 1.0 op_sel:[1,0,0]
	v_pk_fma_f32 v[52:53], v[80:81], v[84:85], v[52:53] op_sel_hi:[0,1,1]
	v_cvt_scalef32_pk_f32_fp4 v[84:85], v79, 1.0 op_sel:[1,0,0]
	v_pk_fma_f32 v[46:47], v[80:81], v[84:85], v[46:47] op_sel_hi:[0,1,1]
	v_cvt_scalef32_pk_f32_fp4 v[84:85], v76, 1.0 op_sel:[0,1,0]
	v_pk_fma_f32 v[70:71], v[80:81], v[84:85], v[70:71] op_sel_hi:[0,1,1]
	v_cvt_scalef32_pk_f32_fp4 v[84:85], v77, 1.0 op_sel:[0,1,0]
	v_pk_fma_f32 v[62:63], v[80:81], v[84:85], v[62:63] op_sel_hi:[0,1,1]
	v_cvt_scalef32_pk_f32_fp4 v[84:85], v78, 1.0 op_sel:[0,1,0]
	v_pk_fma_f32 v[54:55], v[80:81], v[84:85], v[54:55] op_sel_hi:[0,1,1]
	v_cvt_scalef32_pk_f32_fp4 v[84:85], v79, 1.0 op_sel:[0,1,0]
	v_pk_fma_f32 v[48:49], v[80:81], v[84:85], v[48:49] op_sel_hi:[0,1,1]
	v_cvt_scalef32_pk_f32_fp4 v[84:85], v76, 1.0 op_sel:[1,1,0]
	v_cvt_scalef32_pk_f32_fp4 v[76:77], v77, 1.0 op_sel:[1,1,0]
	v_pk_fma_f32 v[64:65], v[80:81], v[76:77], v[64:65] op_sel_hi:[0,1,1]
	v_cvt_scalef32_pk_f32_fp4 v[76:77], v78, 1.0 op_sel:[1,1,0]
	v_pk_fma_f32 v[56:57], v[80:81], v[76:77], v[56:57] op_sel_hi:[0,1,1]
	v_cvt_scalef32_pk_f32_fp4 v[76:77], v79, 1.0 op_sel:[1,1,0]
	v_pk_fma_f32 v[42:43], v[80:81], v[76:77], v[42:43] op_sel_hi:[0,1,1]
	s_waitcnt vmcnt(6)
	v_cvt_scalef32_pk_f32_fp4 v[78:79], v36, 1.0
	v_pk_fma_f32 v[68:69], v[82:83], v[78:79], v[68:69] op_sel_hi:[0,1,1]
	v_cvt_scalef32_pk_f32_fp4 v[78:79], v37, 1.0
	v_pk_fma_f32 v[58:59], v[82:83], v[78:79], v[58:59] op_sel_hi:[0,1,1]
	v_cvt_scalef32_pk_f32_fp4 v[78:79], v38, 1.0
	v_pk_fma_f32 v[50:51], v[82:83], v[78:79], v[50:51] op_sel_hi:[0,1,1]
	v_cvt_scalef32_pk_f32_fp4 v[78:79], v39, 1.0
	v_pk_fma_f32 v[44:45], v[82:83], v[78:79], v[44:45] op_sel_hi:[0,1,1]
	v_cvt_scalef32_pk_f32_fp4 v[78:79], v36, 1.0 op_sel:[1,0,0]
	v_pk_fma_f32 v[66:67], v[82:83], v[78:79], v[66:67] op_sel_hi:[0,1,1]
	v_cvt_scalef32_pk_f32_fp4 v[78:79], v37, 1.0 op_sel:[1,0,0]
	v_pk_fma_f32 v[60:61], v[82:83], v[78:79], v[60:61] op_sel_hi:[0,1,1]
	v_cvt_scalef32_pk_f32_fp4 v[78:79], v38, 1.0 op_sel:[1,0,0]
	v_pk_fma_f32 v[52:53], v[82:83], v[78:79], v[52:53] op_sel_hi:[0,1,1]
	v_cvt_scalef32_pk_f32_fp4 v[78:79], v39, 1.0 op_sel:[1,0,0]
	v_pk_fma_f32 v[46:47], v[82:83], v[78:79], v[46:47] op_sel_hi:[0,1,1]
	v_cvt_scalef32_pk_f32_fp4 v[78:79], v36, 1.0 op_sel:[0,1,0]
	v_pk_fma_f32 v[70:71], v[82:83], v[78:79], v[70:71] op_sel_hi:[0,1,1]
	v_cvt_scalef32_pk_f32_fp4 v[78:79], v37, 1.0 op_sel:[0,1,0]
	v_pk_fma_f32 v[62:63], v[82:83], v[78:79], v[62:63] op_sel_hi:[0,1,1]
	v_cvt_scalef32_pk_f32_fp4 v[78:79], v38, 1.0 op_sel:[0,1,0]
	v_pk_fma_f32 v[54:55], v[82:83], v[78:79], v[54:55] op_sel_hi:[0,1,1]
	v_cvt_scalef32_pk_f32_fp4 v[78:79], v39, 1.0 op_sel:[0,1,0]
	v_pk_fma_f32 v[48:49], v[82:83], v[78:79], v[48:49] op_sel_hi:[0,1,1]
	v_cvt_scalef32_pk_f32_fp4 v[78:79], v36, 1.0 op_sel:[1,1,0]
	v_cvt_scalef32_pk_f32_fp4 v[36:37], v37, 1.0 op_sel:[1,1,0]
	v_pk_fma_f32 v[36:37], v[82:83], v[36:37], v[64:65] op_sel_hi:[0,1,1]
	v_cvt_scalef32_pk_f32_fp4 v[64:65], v38, 1.0 op_sel:[1,1,0]
	v_pk_fma_f32 v[56:57], v[82:83], v[64:65], v[56:57] op_sel_hi:[0,1,1]
	s_waitcnt vmcnt(5)
; #define FP4_AXPY(k) { acc2[k] += w * __builtin_amdgcn_cvt_scalef32_pk_f32_fp4(vr[q].x, 1.0f, k); acc2[4 + k] += w * __builtin_amdgcn_cvt_scalef32_pk_f32_fp4(vr[q].y, 1.0f, k); \
;                       acc2[8 + k] += w * __builtin_amdgcn_cvt_scalef32_pk_f32_fp4(vr[q].z, 1.0f, k); acc2[12 + k] += w * __builtin_amdgcn_cvt_scalef32_pk_f32_fp4(vr[q].w, 1.0f, k); }
; __device__ __forceinline__ void peer_token(const Params& P, int t, int lane, int* sidx, float* sval, const int* sid, const float* sgate, const unsigned* szero) {
;     ...
; #pragma unroll
;         for (int q = 0; q < 8; ++q) {
;             const float w = half ? wq[2 * q + 1] : wq[2 * q];
;     ...
;             FP4_AXPY(0) FP4_AXPY(1) FP4_AXPY(2) FP4_AXPY(3)
;     ...
;         }
	v_cvt_scalef32_pk_f32_fp4 v[64:65], v33, 1.0
	v_pk_fma_f32 v[58:59], v[28:29], v[64:65], v[58:59] op_sel_hi:[0,1,1]
	v_cvt_scalef32_pk_f32_fp4 v[64:65], v34, 1.0
	v_cvt_scalef32_pk_f32_fp4 v[38:39], v39, 1.0 op_sel:[1,1,0]
	v_pk_fma_f32 v[50:51], v[28:29], v[64:65], v[50:51] op_sel_hi:[0,1,1]
	v_cvt_scalef32_pk_f32_fp4 v[64:65], v35, 1.0
	v_pk_fma_f32 v[38:39], v[82:83], v[38:39], v[42:43] op_sel_hi:[0,1,1]
	v_cvt_scalef32_pk_f32_fp4 v[42:43], v32, 1.0
	v_pk_fma_f32 v[44:45], v[28:29], v[64:65], v[44:45] op_sel_hi:[0,1,1]
	v_cvt_scalef32_pk_f32_fp4 v[64:65], v32, 1.0 op_sel:[1,0,0]
	v_pk_fma_f32 v[42:43], v[28:29], v[42:43], v[68:69] op_sel_hi:[0,1,1]
	v_pk_fma_f32 v[64:65], v[28:29], v[64:65], v[66:67] op_sel_hi:[0,1,1]
	v_cvt_scalef32_pk_f32_fp4 v[66:67], v33, 1.0 op_sel:[1,0,0]
	v_cvt_scalef32_pk_f32_fp4 v[68:69], v33, 1.0 op_sel:[0,1,0]
	v_pk_fma_f32 v[60:61], v[28:29], v[66:67], v[60:61] op_sel_hi:[0,1,1]
	v_cvt_scalef32_pk_f32_fp4 v[66:67], v34, 1.0 op_sel:[1,0,0]
	v_pk_fma_f32 v[62:63], v[28:29], v[68:69], v[62:63] op_sel_hi:[0,1,1]
	v_cvt_scalef32_pk_f32_fp4 v[68:69], v34, 1.0 op_sel:[0,1,0]
	v_pk_fma_f32 v[52:53], v[28:29], v[66:67], v[52:53] op_sel_hi:[0,1,1]
	v_cvt_scalef32_pk_f32_fp4 v[66:67], v35, 1.0 op_sel:[1,0,0]
	v_pk_fma_f32 v[54:55], v[28:29], v[68:69], v[54:55] op_sel_hi:[0,1,1]
	v_cvt_scalef32_pk_f32_fp4 v[68:69], v35, 1.0 op_sel:[0,1,0]
	v_pk_fma_f32 v[46:47], v[28:29], v[66:67], v[46:47] op_sel_hi:[0,1,1]
	v_cvt_scalef32_pk_f32_fp4 v[66:67], v32, 1.0 op_sel:[0,1,0]
	v_pk_fma_f32 v[48:49], v[28:29], v[68:69], v[48:49] op_sel_hi:[0,1,1]
	v_cvt_scalef32_pk_f32_fp4 v[68:69], v32, 1.0 op_sel:[1,1,0]
	v_cvt_scalef32_pk_f32_fp4 v[32:33], v33, 1.0 op_sel:[1,1,0]
	v_pk_fma_f32 v[72:73], v[80:81], v[84:85], v[72:73] op_sel_hi:[0,1,1]
	v_pk_fma_f32 v[32:33], v[28:29], v[32:33], v[36:37] op_sel_hi:[0,1,1]
	v_cvt_scalef32_pk_f32_fp4 v[36:37], v34, 1.0 op_sel:[1,1,0]
	v_pk_fma_f32 v[72:73], v[82:83], v[78:79], v[72:73] op_sel_hi:[0,1,1]
	v_pk_fma_f32 v[36:37], v[28:29], v[36:37], v[56:57] op_sel_hi:[0,1,1]
	v_cvt_scalef32_pk_f32_fp4 v[34:35], v35, 1.0 op_sel:[1,1,0]
	s_waitcnt vmcnt(4)
	v_cvt_scalef32_pk_f32_fp4 v[56:57], v25, 1.0 op_sel:[1,0,0]
	v_pk_fma_f32 v[66:67], v[28:29], v[66:67], v[70:71] op_sel_hi:[0,1,1]
	v_pk_fma_f32 v[68:69], v[28:29], v[68:69], v[72:73] op_sel_hi:[0,1,1]
	v_pk_fma_f32 v[28:29], v[28:29], v[34:35], v[38:39] op_sel_hi:[0,1,1]
	v_cvt_scalef32_pk_f32_fp4 v[34:35], v24, 1.0
	v_cvt_scalef32_pk_f32_fp4 v[38:39], v25, 1.0
	v_pk_fma_f32 v[56:57], v[30:31], v[56:57], v[60:61] op_sel_hi:[0,1,1]
	v_cvt_scalef32_pk_f32_fp4 v[60:61], v25, 1.0 op_sel:[0,1,0]
	v_pk_fma_f32 v[34:35], v[30:31], v[34:35], v[42:43] op_sel_hi:[0,1,1]
	v_pk_fma_f32 v[38:39], v[30:31], v[38:39], v[58:59] op_sel_hi:[0,1,1]
	v_cvt_scalef32_pk_f32_fp4 v[42:43], v26, 1.0
	v_cvt_scalef32_pk_f32_fp4 v[58:59], v26, 1.0 op_sel:[1,0,0]
	v_pk_fma_f32 v[60:61], v[30:31], v[60:61], v[62:63] op_sel_hi:[0,1,1]
	v_cvt_scalef32_pk_f32_fp4 v[62:63], v26, 1.0 op_sel:[0,1,0]
	v_pk_fma_f32 v[42:43], v[30:31], v[42:43], v[50:51] op_sel_hi:[0,1,1]
	v_cvt_scalef32_pk_f32_fp4 v[50:51], v27, 1.0
	v_pk_fma_f32 v[52:53], v[30:31], v[58:59], v[52:53] op_sel_hi:[0,1,1]
	v_cvt_scalef32_pk_f32_fp4 v[58:59], v27, 1.0 op_sel:[1,0,0]
	v_pk_fma_f32 v[54:55], v[30:31], v[62:63], v[54:55] op_sel_hi:[0,1,1]
	v_cvt_scalef32_pk_f32_fp4 v[62:63], v27, 1.0 op_sel:[0,1,0]
	v_pk_fma_f32 v[44:45], v[30:31], v[50:51], v[44:45] op_sel_hi:[0,1,1]
	v_cvt_scalef32_pk_f32_fp4 v[50:51], v24, 1.0 op_sel:[1,0,0]
	v_pk_fma_f32 v[46:47], v[30:31], v[58:59], v[46:47] op_sel_hi:[0,1,1]
	v_cvt_scalef32_pk_f32_fp4 v[58:59], v24, 1.0 op_sel:[0,1,0]
	v_pk_fma_f32 v[48:49], v[30:31], v[62:63], v[48:49] op_sel_hi:[0,1,1]
	v_cvt_scalef32_pk_f32_fp4 v[62:63], v24, 1.0 op_sel:[1,1,0]
	v_cvt_scalef32_pk_f32_fp4 v[24:25], v25, 1.0 op_sel:[1,1,0]
	v_pk_fma_f32 v[24:25], v[30:31], v[24:25], v[32:33] op_sel_hi:[0,1,1]
	v_cvt_scalef32_pk_f32_fp4 v[32:33], v26, 1.0 op_sel:[1,1,0]
	v_cvt_scalef32_pk_f32_fp4 v[26:27], v27, 1.0 op_sel:[1,1,0]
	v_pk_fma_f32 v[26:27], v[30:31], v[26:27], v[28:29] op_sel_hi:[0,1,1]
	s_waitcnt vmcnt(3)
	v_cvt_scalef32_pk_f32_fp4 v[28:29], v20, 1.0
	v_pk_fma_f32 v[28:29], v[16:17], v[28:29], v[34:35] op_sel_hi:[0,1,1]
	v_cvt_scalef32_pk_f32_fp4 v[34:35], v22, 1.0
	v_pk_fma_f32 v[50:51], v[30:31], v[50:51], v[64:65] op_sel_hi:[0,1,1]
	v_pk_fma_f32 v[58:59], v[30:31], v[58:59], v[66:67] op_sel_hi:[0,1,1]
	v_pk_fma_f32 v[62:63], v[30:31], v[62:63], v[68:69] op_sel_hi:[0,1,1]
	v_pk_fma_f32 v[32:33], v[30:31], v[32:33], v[36:37] op_sel_hi:[0,1,1]
	v_cvt_scalef32_pk_f32_fp4 v[30:31], v21, 1.0
	v_pk_fma_f32 v[34:35], v[16:17], v[34:35], v[42:43] op_sel_hi:[0,1,1]
	v_cvt_scalef32_pk_f32_fp4 v[42:43], v21, 1.0 op_sel:[1,0,0]
	v_pk_fma_f32 v[30:31], v[16:17], v[30:31], v[38:39] op_sel_hi:[0,1,1]
	v_cvt_scalef32_pk_f32_fp4 v[36:37], v23, 1.0
	v_cvt_scalef32_pk_f32_fp4 v[38:39], v20, 1.0 op_sel:[1,0,0]
	v_pk_fma_f32 v[42:43], v[16:17], v[42:43], v[56:57] op_sel_hi:[0,1,1]
	v_cvt_scalef32_pk_f32_fp4 v[56:57], v22, 1.0 op_sel:[0,1,0]
	v_pk_fma_f32 v[36:37], v[16:17], v[36:37], v[44:45] op_sel_hi:[0,1,1]
	v_pk_fma_f32 v[38:39], v[16:17], v[38:39], v[50:51] op_sel_hi:[0,1,1]
	v_cvt_scalef32_pk_f32_fp4 v[44:45], v22, 1.0 op_sel:[1,0,0]
	v_cvt_scalef32_pk_f32_fp4 v[50:51], v23, 1.0 op_sel:[1,0,0]
	v_pk_fma_f32 v[54:55], v[16:17], v[56:57], v[54:55] op_sel_hi:[0,1,1]
	v_cvt_scalef32_pk_f32_fp4 v[56:57], v23, 1.0 op_sel:[0,1,0]
	v_pk_fma_f32 v[44:45], v[16:17], v[44:45], v[52:53] op_sel_hi:[0,1,1]
	v_pk_fma_f32 v[46:47], v[16:17], v[50:51], v[46:47] op_sel_hi:[0,1,1]
	v_cvt_scalef32_pk_f32_fp4 v[50:51], v20, 1.0 op_sel:[0,1,0]
	v_cvt_scalef32_pk_f32_fp4 v[52:53], v21, 1.0 op_sel:[0,1,0]
	v_pk_fma_f32 v[48:49], v[16:17], v[56:57], v[48:49] op_sel_hi:[0,1,1]
	v_cvt_scalef32_pk_f32_fp4 v[56:57], v20, 1.0 op_sel:[1,1,0]
	v_cvt_scalef32_pk_f32_fp4 v[20:21], v21, 1.0 op_sel:[1,1,0]
	v_pk_fma_f32 v[20:21], v[16:17], v[20:21], v[24:25] op_sel_hi:[0,1,1]
	v_cvt_scalef32_pk_f32_fp4 v[24:25], v22, 1.0 op_sel:[1,1,0]
	v_pk_fma_f32 v[24:25], v[16:17], v[24:25], v[32:33] op_sel_hi:[0,1,1]
	s_waitcnt vmcnt(2)
; #define FP4_AXPY(k) { acc2[k] += w * __builtin_amdgcn_cvt_scalef32_pk_f32_fp4(vr[q].x, 1.0f, k); acc2[4 + k] += w * __builtin_amdgcn_cvt_scalef32_pk_f32_fp4(vr[q].y, 1.0f, k); \
;                       acc2[8 + k] += w * __builtin_amdgcn_cvt_scalef32_pk_f32_fp4(vr[q].z, 1.0f, k); acc2[12 + k] += w * __builtin_amdgcn_cvt_scalef32_pk_f32_fp4(vr[q].w, 1.0f, k); }
; __device__ __forceinline__ void peer_token(const Params& P, int t, int lane, int* sidx, float* sval, const int* sid, const float* sgate, const unsigned* szero) {
;     ...
; #pragma unroll
;         for (int q = 0; q < 8; ++q) {
;             const float w = half ? wq[2 * q + 1] : wq[2 * q];
;     ...
;             FP4_AXPY(0) FP4_AXPY(1) FP4_AXPY(2) FP4_AXPY(3)
;     ...
;         }
	v_cvt_scalef32_pk_f32_fp4 v[32:33], v12, 1.0 op_sel:[1,0,0]
	v_pk_fma_f32 v[50:51], v[16:17], v[50:51], v[58:59] op_sel_hi:[0,1,1]
	v_pk_fma_f32 v[58:59], v[18:19], v[32:33], v[38:39] op_sel_hi:[0,1,1]
	v_cvt_scalef32_pk_f32_fp4 v[32:33], v13, 1.0 op_sel:[1,0,0]
	v_pk_fma_f32 v[42:43], v[18:19], v[32:33], v[42:43] op_sel_hi:[0,1,1]
	v_cvt_scalef32_pk_f32_fp4 v[32:33], v14, 1.0 op_sel:[1,0,0]
	v_pk_fma_f32 v[44:45], v[18:19], v[32:33], v[44:45] op_sel_hi:[0,1,1]
	v_cvt_scalef32_pk_f32_fp4 v[32:33], v15, 1.0 op_sel:[1,0,0]
	v_pk_fma_f32 v[46:47], v[18:19], v[32:33], v[46:47] op_sel_hi:[0,1,1]
	v_cvt_scalef32_pk_f32_fp4 v[32:33], v12, 1.0 op_sel:[0,1,0]
	v_pk_fma_f32 v[52:53], v[16:17], v[52:53], v[60:61] op_sel_hi:[0,1,1]
	v_pk_fma_f32 v[50:51], v[18:19], v[32:33], v[50:51] op_sel_hi:[0,1,1]
	v_cvt_scalef32_pk_f32_fp4 v[32:33], v13, 1.0 op_sel:[0,1,0]
	v_pk_fma_f32 v[52:53], v[18:19], v[32:33], v[52:53] op_sel_hi:[0,1,1]
	v_cvt_scalef32_pk_f32_fp4 v[32:33], v14, 1.0 op_sel:[0,1,0]
	v_cvt_scalef32_pk_f32_fp4 v[22:23], v23, 1.0 op_sel:[1,1,0]
	v_pk_fma_f32 v[54:55], v[18:19], v[32:33], v[54:55] op_sel_hi:[0,1,1]
	v_cvt_scalef32_pk_f32_fp4 v[32:33], v15, 1.0 op_sel:[0,1,0]
	v_pk_fma_f32 v[56:57], v[16:17], v[56:57], v[62:63] op_sel_hi:[0,1,1]
	v_pk_fma_f32 v[16:17], v[16:17], v[22:23], v[26:27] op_sel_hi:[0,1,1]
	v_cvt_scalef32_pk_f32_fp4 v[22:23], v12, 1.0
	v_cvt_scalef32_pk_f32_fp4 v[26:27], v13, 1.0
	v_pk_fma_f32 v[48:49], v[18:19], v[32:33], v[48:49] op_sel_hi:[0,1,1]
	v_cvt_scalef32_pk_f32_fp4 v[32:33], v12, 1.0 op_sel:[1,1,0]
	v_cvt_scalef32_pk_f32_fp4 v[12:13], v13, 1.0 op_sel:[1,1,0]
	v_pk_fma_f32 v[22:23], v[18:19], v[22:23], v[28:29] op_sel_hi:[0,1,1]
	v_pk_fma_f32 v[26:27], v[18:19], v[26:27], v[30:31] op_sel_hi:[0,1,1]
	v_cvt_scalef32_pk_f32_fp4 v[28:29], v14, 1.0
	v_cvt_scalef32_pk_f32_fp4 v[30:31], v15, 1.0
	v_pk_fma_f32 v[12:13], v[18:19], v[12:13], v[20:21] op_sel_hi:[0,1,1]
	v_cvt_scalef32_pk_f32_fp4 v[20:21], v14, 1.0 op_sel:[1,1,0]
	v_cvt_scalef32_pk_f32_fp4 v[14:15], v15, 1.0 op_sel:[1,1,0]
	v_pk_fma_f32 v[62:63], v[18:19], v[14:15], v[16:17] op_sel_hi:[0,1,1]
	s_waitcnt vmcnt(1)
	v_cvt_scalef32_pk_f32_fp4 v[14:15], v8, 1.0
	s_waitcnt lgkmcnt(0)
	v_pk_fma_f32 v[38:39], v[4:5], v[14:15], v[22:23] op_sel_hi:[0,1,1]
	v_cvt_scalef32_pk_f32_fp4 v[14:15], v9, 1.0
	v_pk_fma_f32 v[28:29], v[18:19], v[28:29], v[34:35] op_sel_hi:[0,1,1]
	v_pk_fma_f32 v[30:31], v[18:19], v[30:31], v[36:37] op_sel_hi:[0,1,1]
	v_pk_fma_f32 v[36:37], v[4:5], v[14:15], v[26:27] op_sel_hi:[0,1,1]
	v_cvt_scalef32_pk_f32_fp4 v[14:15], v10, 1.0
	v_pk_fma_f32 v[34:35], v[4:5], v[14:15], v[28:29] op_sel_hi:[0,1,1]
	v_cvt_scalef32_pk_f32_fp4 v[14:15], v11, 1.0
	v_pk_fma_f32 v[56:57], v[18:19], v[32:33], v[56:57] op_sel_hi:[0,1,1]
	v_pk_fma_f32 v[32:33], v[4:5], v[14:15], v[30:31] op_sel_hi:[0,1,1]
	v_cvt_scalef32_pk_f32_fp4 v[14:15], v8, 1.0 op_sel:[1,0,0]
	v_pk_fma_f32 v[30:31], v[4:5], v[14:15], v[58:59] op_sel_hi:[0,1,1]
	v_cvt_scalef32_pk_f32_fp4 v[14:15], v9, 1.0 op_sel:[1,0,0]
	v_pk_fma_f32 v[28:29], v[4:5], v[14:15], v[42:43] op_sel_hi:[0,1,1]
	v_cvt_scalef32_pk_f32_fp4 v[14:15], v10, 1.0 op_sel:[1,0,0]
	v_pk_fma_f32 v[26:27], v[4:5], v[14:15], v[44:45] op_sel_hi:[0,1,1]
	v_cvt_scalef32_pk_f32_fp4 v[14:15], v11, 1.0 op_sel:[1,0,0]
	v_pk_fma_f32 v[60:61], v[18:19], v[20:21], v[24:25] op_sel_hi:[0,1,1]
	v_pk_fma_f32 v[24:25], v[4:5], v[14:15], v[46:47] op_sel_hi:[0,1,1]
	v_cvt_scalef32_pk_f32_fp4 v[14:15], v8, 1.0 op_sel:[0,1,0]
	v_pk_fma_f32 v[22:23], v[4:5], v[14:15], v[50:51] op_sel_hi:[0,1,1]
	v_cvt_scalef32_pk_f32_fp4 v[14:15], v9, 1.0 op_sel:[0,1,0]
	v_pk_fma_f32 v[20:21], v[4:5], v[14:15], v[52:53] op_sel_hi:[0,1,1]
	v_cvt_scalef32_pk_f32_fp4 v[14:15], v10, 1.0 op_sel:[0,1,0]
	v_pk_fma_f32 v[18:19], v[4:5], v[14:15], v[54:55] op_sel_hi:[0,1,1]
	v_cvt_scalef32_pk_f32_fp4 v[14:15], v11, 1.0 op_sel:[0,1,0]
	v_pk_fma_f32 v[16:17], v[4:5], v[14:15], v[48:49] op_sel_hi:[0,1,1]
	v_cvt_scalef32_pk_f32_fp4 v[14:15], v8, 1.0 op_sel:[1,1,0]
	v_cvt_scalef32_pk_f32_fp4 v[8:9], v9, 1.0 op_sel:[1,1,0]
	v_pk_fma_f32 v[12:13], v[4:5], v[8:9], v[12:13] op_sel_hi:[0,1,1]
	v_cvt_scalef32_pk_f32_fp4 v[8:9], v10, 1.0 op_sel:[1,1,0]
	v_cvt_scalef32_pk_f32_fp4 v[10:11], v11, 1.0 op_sel:[1,1,0]
	v_pk_fma_f32 v[14:15], v[4:5], v[14:15], v[56:57] op_sel_hi:[0,1,1]
	v_pk_fma_f32 v[8:9], v[4:5], v[8:9], v[60:61] op_sel_hi:[0,1,1]
	v_pk_fma_f32 v[4:5], v[4:5], v[10:11], v[62:63] op_sel_hi:[0,1,1]
	s_waitcnt vmcnt(0)
	v_cvt_scalef32_pk_f32_fp4 v[10:11], v0, 1.0
	v_pk_fma_f32 v[68:69], v[6:7], v[10:11], v[38:39] op_sel_hi:[0,1,1]
	v_cvt_scalef32_pk_f32_fp4 v[10:11], v1, 1.0
	v_pk_fma_f32 v[58:59], v[6:7], v[10:11], v[36:37] op_sel_hi:[0,1,1]
	v_cvt_scalef32_pk_f32_fp4 v[10:11], v2, 1.0
	v_pk_fma_f32 v[50:51], v[6:7], v[10:11], v[34:35] op_sel_hi:[0,1,1]
	v_cvt_scalef32_pk_f32_fp4 v[10:11], v3, 1.0
	v_pk_fma_f32 v[44:45], v[6:7], v[10:11], v[32:33] op_sel_hi:[0,1,1]
	v_cvt_scalef32_pk_f32_fp4 v[10:11], v0, 1.0 op_sel:[1,0,0]
	v_pk_fma_f32 v[66:67], v[6:7], v[10:11], v[30:31] op_sel_hi:[0,1,1]
	v_cvt_scalef32_pk_f32_fp4 v[10:11], v1, 1.0 op_sel:[1,0,0]
	v_pk_fma_f32 v[60:61], v[6:7], v[10:11], v[28:29] op_sel_hi:[0,1,1]
	v_cvt_scalef32_pk_f32_fp4 v[10:11], v2, 1.0 op_sel:[1,0,0]
	v_pk_fma_f32 v[52:53], v[6:7], v[10:11], v[26:27] op_sel_hi:[0,1,1]
	v_cvt_scalef32_pk_f32_fp4 v[10:11], v3, 1.0 op_sel:[1,0,0]
	v_pk_fma_f32 v[46:47], v[6:7], v[10:11], v[24:25] op_sel_hi:[0,1,1]
	v_cvt_scalef32_pk_f32_fp4 v[10:11], v0, 1.0 op_sel:[0,1,0]
	v_pk_fma_f32 v[70:71], v[6:7], v[10:11], v[22:23] op_sel_hi:[0,1,1]
	v_cvt_scalef32_pk_f32_fp4 v[10:11], v1, 1.0 op_sel:[0,1,0]
	v_pk_fma_f32 v[62:63], v[6:7], v[10:11], v[20:21] op_sel_hi:[0,1,1]
	v_cvt_scalef32_pk_f32_fp4 v[10:11], v2, 1.0 op_sel:[0,1,0]
	v_pk_fma_f32 v[54:55], v[6:7], v[10:11], v[18:19] op_sel_hi:[0,1,1]
	v_cvt_scalef32_pk_f32_fp4 v[10:11], v3, 1.0 op_sel:[0,1,0]
	v_pk_fma_f32 v[48:49], v[6:7], v[10:11], v[16:17] op_sel_hi:[0,1,1]
	v_cvt_scalef32_pk_f32_fp4 v[10:11], v0, 1.0 op_sel:[1,1,0]
	v_cvt_scalef32_pk_f32_fp4 v[0:1], v1, 1.0 op_sel:[1,1,0]
	v_pk_fma_f32 v[64:65], v[6:7], v[0:1], v[12:13] op_sel_hi:[0,1,1]
	v_cvt_scalef32_pk_f32_fp4 v[0:1], v2, 1.0 op_sel:[1,1,0]
	v_pk_fma_f32 v[56:57], v[6:7], v[0:1], v[8:9] op_sel_hi:[0,1,1]
	v_cvt_scalef32_pk_f32_fp4 v[0:1], v3, 1.0 op_sel:[1,1,0]
	v_pk_fma_f32 v[72:73], v[6:7], v[10:11], v[14:15] op_sel_hi:[0,1,1]
	v_pk_fma_f32 v[42:43], v[6:7], v[0:1], v[4:5] op_sel_hi:[0,1,1]
	s_cbranch_scc1 .LBB0_1424
; __device__ __forceinline__ void peer_token(const Params& P, int t, int lane, int* sidx, float* sval, const int* sid, const float* sgate, const unsigned* szero) {
;     ...
;     f32x2 acc[8];
; #pragma unroll
;     for (int j = 0; j < 16; ++j) {
;         const unsigned x0 = __float_as_uint(acc2[j].x), x1 = __float_as_uint(acc2[j].y);
;         const auto r0 = __builtin_amdgcn_permlane32_swap(x0, x0, false, false);
;         const auto r1 = __builtin_amdgcn_permlane32_swap(x1, x1, false, false);
;         acc2[j].x = __uint_as_float(r0[0]) + __uint_as_float(r0[1]);
;         acc2[j].y = __uint_as_float(r1[0]) + __uint_as_float(r1[1]);
;     }
; #pragma unroll
;     for (int j = 0; j < 8; ++j) { acc[j].x = half ? acc2[8 + j].x : acc2[j].x; acc[j].y = half ? acc2[8 + j].y : acc2[j].y; }
;     f32x2 xf[8];
;     {
;         const uint4 xa = *(const uint4*)(xn + lane_o * 16), xb = *(const uint4*)(xn + lane_o * 16 + 8);
;         xf[0] = (f32x2){bflo(xa.x), bfhi(xa.x)}; xf[1] = (f32x2){bflo(xa.y), bfhi(xa.y)}; xf[2] = (f32x2){bflo(xa.z), bfhi(xa.z)}; xf[3] = (f32x2){bflo(xa.w), bfhi(xa.w)};
;         xf[4] = (f32x2){bflo(xb.x), bfhi(xb.x)}; xf[5] = (f32x2){bflo(xb.y), bfhi(xb.y)}; xf[6] = (f32x2){bflo(xb.z), bfhi(xb.z)}; xf[7] = (f32x2){bflo(xb.w), bfhi(xb.w)};
;     }
;     float* o = P.out + (size_t)t * DM + lane_o * 16;
;     float4 h0, h1, h2, h3;
;     {
;         const float4 g0 = *(const float4*)(P.norm_ffn + lane_o * 16), g1 = *(const float4*)(P.norm_ffn + lane_o * 16 + 4), g2 = *(const float4*)(P.norm_ffn + lane_o * 16 + 8), g3 = *(const float4*)(P.norm_ffn + lane_o * 16 + 12);
;         h0.x = xf[0].x * __builtin_amdgcn_rcpf(g0.x) + acc[0].x; h0.y = xf[0].y * __builtin_amdgcn_rcpf(g0.y) + acc[0].y; h0.z = xf[1].x * __builtin_amdgcn_rcpf(g0.z) + acc[1].x; h0.w = xf[1].y * __builtin_amdgcn_rcpf(g0.w) + acc[1].y;
;         h1.x = xf[2].x * __builtin_amdgcn_rcpf(g1.x) + acc[2].x; h1.y = xf[2].y * __builtin_amdgcn_rcpf(g1.y) + acc[2].y; h1.z = xf[3].x * __builtin_amdgcn_rcpf(g1.z) + acc[3].x; h1.w = xf[3].y * __builtin_amdgcn_rcpf(g1.w) + acc[3].y;
;         h2.x = xf[4].x * __builtin_amdgcn_rcpf(g2.x) + acc[4].x; h2.y = xf[4].y * __builtin_amdgcn_rcpf(g2.y) + acc[4].y; h2.z = xf[5].x * __builtin_amdgcn_rcpf(g2.z) + acc[5].x; h2.w = xf[5].y * __builtin_amdgcn_rcpf(g2.w) + acc[5].y;
	v_lshl_add_u64 v[0:1], v[104:105], 1, v[110:111]
	global_load_dwordx4 v[2:5], v[108:109], off
	global_load_dwordx4 v[6:9], v[108:109], off offset:16
	global_load_dwordx4 v[10:13], v[0:1], off
	global_load_dwordx4 v[14:17], v[0:1], off offset:16
	global_load_dwordx4 v[18:21], v[108:109], off offset:32
	global_load_dwordx4 v[22:25], v[108:109], off offset:48
	v_mov_b32_e32 v26, v68
	v_mov_b32_e32 v27, v69
	v_mov_b32_e32 v29, v67
	v_mov_b32_e32 v77, v51
	v_mov_b32_e32 v79, v53
	v_mov_b32_e32 v28, v66
	v_mov_b32_e32 v76, v50
	v_mov_b32_e32 v78, v52
	v_mov_b32_e32 v31, v71
	v_mov_b32_e32 v33, v73
	v_mov_b32_e32 v35, v59
	v_mov_b32_e32 v37, v61
	v_mov_b32_e32 v39, v63
	v_mov_b32_e32 v75, v65
	v_mov_b32_e32 v81, v55
	v_mov_b32_e32 v83, v57
	v_mov_b32_e32 v85, v45
	v_mov_b32_e32 v87, v47
	v_mov_b32_e32 v89, v49
	v_mov_b32_e32 v91, v43
	v_permlane32_swap_b32_e32 v68, v26
	v_permlane32_swap_b32_e32 v69, v27
	v_permlane32_swap_b32_e32 v67, v29
	v_permlane32_swap_b32_e32 v51, v77
	v_permlane32_swap_b32_e32 v53, v79
	v_permlane32_swap_b32_e32 v66, v28
	v_mov_b32_e32 v30, v70
	v_mov_b32_e32 v32, v72
	v_mov_b32_e32 v34, v58
	v_mov_b32_e32 v36, v60
	v_mov_b32_e32 v38, v62
	v_mov_b32_e32 v74, v64
	v_permlane32_swap_b32_e32 v50, v76
	v_permlane32_swap_b32_e32 v52, v78
	v_mov_b32_e32 v80, v54
	v_mov_b32_e32 v82, v56
	v_mov_b32_e32 v84, v44
	v_mov_b32_e32 v86, v46
	v_mov_b32_e32 v88, v48
	v_mov_b32_e32 v90, v42
	v_permlane32_swap_b32_e32 v71, v31
	v_permlane32_swap_b32_e32 v73, v33
	v_permlane32_swap_b32_e32 v59, v35
	v_permlane32_swap_b32_e32 v61, v37
	v_permlane32_swap_b32_e32 v63, v39
	v_permlane32_swap_b32_e32 v65, v75
	v_permlane32_swap_b32_e32 v55, v81
	v_permlane32_swap_b32_e32 v57, v83
	v_permlane32_swap_b32_e32 v45, v85
	v_permlane32_swap_b32_e32 v47, v87
	v_permlane32_swap_b32_e32 v49, v89
	v_permlane32_swap_b32_e32 v43, v91
	v_pk_add_f32 v[26:27], v[68:69], v[26:27]
	v_pk_add_f32 v[28:29], v[66:67], v[28:29]
	v_permlane32_swap_b32_e32 v70, v30
	v_permlane32_swap_b32_e32 v72, v32
	s_waitcnt vmcnt(5)
	v_rcp_f32_e32 v2, v2
	v_rcp_f32_e32 v3, v3
	v_rcp_f32_e32 v4, v4
	v_rcp_f32_e32 v5, v5
	s_waitcnt vmcnt(4)
	v_rcp_f32_e32 v6, v6
	v_rcp_f32_e32 v7, v7
	v_rcp_f32_e32 v8, v8
	v_rcp_f32_e32 v9, v9
	s_waitcnt vmcnt(1)
	v_rcp_f32_e32 v18, v18
	v_rcp_f32_e32 v19, v19
	v_rcp_f32_e32 v20, v20
	v_rcp_f32_e32 v21, v21
	s_waitcnt vmcnt(0)
	v_rcp_f32_e32 v22, v22
	v_rcp_f32_e32 v23, v23
	v_rcp_f32_e32 v24, v24
	v_rcp_f32_e32 v25, v25
	v_permlane32_swap_b32_e32 v58, v34
	v_permlane32_swap_b32_e32 v60, v36
	v_permlane32_swap_b32_e32 v62, v38
	v_permlane32_swap_b32_e32 v64, v74
	v_pk_add_f32 v[50:51], v[50:51], v[76:77]
	v_pk_add_f32 v[52:53], v[52:53], v[78:79]
	v_permlane32_swap_b32_e32 v54, v80
	v_permlane32_swap_b32_e32 v56, v82
	v_permlane32_swap_b32_e32 v44, v84
	v_permlane32_swap_b32_e32 v46, v86
	v_permlane32_swap_b32_e32 v48, v88
	v_permlane32_swap_b32_e32 v42, v90
	v_lshl_add_u64 v[0:1], v[40:41], 2, v[106:107]
	v_lshlrev_b32_e32 v40, 16, v10
	v_and_b32_e32 v41, 0xffff0000, v10
	v_lshlrev_b32_e32 v10, 16, v11
	v_and_b32_e32 v11, 0xffff0000, v11
	v_pk_add_f32 v[30:31], v[70:71], v[30:31]
	v_pk_add_f32 v[32:33], v[72:73], v[32:33]
	v_pk_add_f32 v[34:35], v[58:59], v[34:35]
	v_pk_add_f32 v[36:37], v[60:61], v[36:37]
	v_pk_add_f32 v[38:39], v[62:63], v[38:39]
	v_pk_add_f32 v[58:59], v[64:65], v[74:75]
	v_pk_add_f32 v[54:55], v[54:55], v[80:81]
	v_pk_add_f32 v[56:57], v[56:57], v[82:83]
	v_pk_add_f32 v[44:45], v[44:45], v[84:85]
	v_pk_add_f32 v[46:47], v[46:47], v[86:87]
	v_pk_add_f32 v[48:49], v[48:49], v[88:89]
	v_pk_add_f32 v[42:43], v[42:43], v[90:91]
	v_cndmask_b32_e64 v27, v51, v27, s[0:1]
	v_cndmask_b32_e64 v26, v50, v26, s[0:1]
	v_cndmask_b32_e64 v29, v53, v29, s[0:1]
	v_cndmask_b32_e64 v28, v52, v28, s[0:1]
	v_lshlrev_b32_e32 v92, 16, v12
	v_and_b32_e32 v93, 0xffff0000, v12
	v_lshlrev_b32_e32 v12, 16, v13
	v_and_b32_e32 v13, 0xffff0000, v13
	v_lshlrev_b32_e32 v94, 16, v14
	v_and_b32_e32 v95, 0xffff0000, v14
	v_lshlrev_b32_e32 v14, 16, v15
	v_and_b32_e32 v15, 0xffff0000, v15
	v_lshlrev_b32_e32 v96, 16, v16
	v_and_b32_e32 v97, 0xffff0000, v16
	v_lshlrev_b32_e32 v16, 16, v17
	v_and_b32_e32 v17, 0xffff0000, v17
	v_cndmask_b32_e64 v31, v55, v31, s[0:1]
	v_cndmask_b32_e64 v30, v54, v30, s[0:1]
	v_cndmask_b32_e64 v33, v57, v33, s[0:1]
	v_cndmask_b32_e64 v32, v56, v32, s[0:1]
	v_cndmask_b32_e64 v35, v45, v35, s[0:1]
	v_cndmask_b32_e64 v34, v44, v34, s[0:1]
	v_cndmask_b32_e64 v37, v47, v37, s[0:1]
	v_cndmask_b32_e64 v36, v46, v36, s[0:1]
	v_cndmask_b32_e64 v39, v49, v39, s[0:1]
	v_cndmask_b32_e64 v38, v48, v38, s[0:1]
	v_cndmask_b32_e64 v43, v43, v59, s[0:1]
	v_cndmask_b32_e64 v42, v42, v58, s[0:1]
	v_pk_fma_f32 v[2:3], v[2:3], v[40:41], v[26:27]
	v_pk_fma_f32 v[4:5], v[4:5], v[10:11], v[28:29]
	v_pk_fma_f32 v[6:7], v[6:7], v[92:93], v[30:31]
	v_pk_fma_f32 v[8:9], v[8:9], v[12:13], v[32:33]
	v_pk_fma_f32 v[10:11], v[18:19], v[94:95], v[34:35]
	v_pk_fma_f32 v[12:13], v[20:21], v[14:15], v[36:37]
	v_pk_fma_f32 v[14:15], v[22:23], v[96:97], v[38:39]
	v_pk_fma_f32 v[16:17], v[24:25], v[16:17], v[42:43]
	global_store_dwordx4 v[0:1], v[2:5], off
	global_store_dwordx4 v[0:1], v[6:9], off offset:16
	global_store_dwordx4 v[0:1], v[10:13], off offset:32
	global_store_dwordx4 v[0:1], v[14:17], off offset:48
